# P10 output stores sc1 nt instead of nt, on top of v102
# speedup vs baseline: 1.0033x; 1.0033x over previous
.LBB0_1035:
	s_ashr_i32 s5, s4, 31
	s_lshl_b64 s[0:1], s[4:5], 6
	s_waitcnt vmcnt(12)
	v_lshl_add_u64 v[32:33], v[52:53], 0, s[0:1]
	s_waitcnt lgkmcnt(0)
	global_load_dwordx4 v[88:91], v[32:33], off
	v_lshl_add_u64 v[32:33], v[54:55], 0, s[0:1]
	global_load_dwordx4 v[92:95], v[32:33], off
	s_add_i32 s6, s12, s4
	s_cmp_lt_i32 s6, 0x8000
	s_cselect_b32 s0, s6, s4
	s_ashr_i32 s1, s0, 31
	s_lshl_b64 s[2:3], s[0:1], 6
	v_lshl_add_u64 v[32:33], v[52:53], 0, s[2:3]
	global_load_dwordx4 v[96:99], v[32:33], off
	v_lshl_add_u64 v[32:33], v[54:55], 0, s[2:3]
	global_load_dwordx4 v[100:103], v[32:33], off
	s_lshl_b64 s[8:9], s[4:5], 12
	s_lshl_b64 s[2:3], s[4:5], 11
	v_lshl_add_u64 v[36:37], v[56:57], 0, s[8:9]
	v_lshl_add_u64 v[32:33], v[60:61], 0, s[2:3]
	v_lshl_add_u64 v[34:35], v[58:59], 0, s[2:3]
	global_load_dwordx4 v[48:51], v[36:37], off offset:3072 nt
	global_load_dwordx4 v[104:107], v[36:37], off offset:2048 nt
	global_load_dwordx2 v[80:81], v[32:33], off offset:1536 nt
	global_load_dwordx2 v[116:117], v[32:33], off offset:1024 nt
	global_load_dwordx2 v[118:119], v[32:33], off offset:512 nt
	global_load_dwordx2 v[120:121], v[32:33], off nt
	global_load_dwordx2 v[82:83], v[34:35], off offset:1536 nt
	global_load_dwordx2 v[122:123], v[34:35], off offset:1024 nt
	global_load_dwordx2 v[124:125], v[34:35], off offset:512 nt
	global_load_dwordx2 v[126:127], v[34:35], off nt
	global_load_dwordx4 v[108:111], v[36:37], off offset:1024 nt
	global_load_dwordx4 v[112:115], v[36:37], off nt
	s_lshl_b64 s[2:3], s[0:1], 12
	s_lshl_b64 s[0:1], s[0:1], 11
	s_waitcnt vmcnt(20)
	v_lshl_add_u64 v[64:65], v[56:57], 0, s[2:3]
	v_lshl_add_u64 v[68:69], v[58:59], 0, s[0:1]
	v_lshl_add_u64 v[128:129], v[60:61], 0, s[0:1]
	global_load_dwordx4 v[44:47], v[64:65], off nt
	global_load_dwordx4 v[40:43], v[64:65], off offset:1024 nt
	global_load_dwordx4 v[36:39], v[64:65], off offset:2048 nt
	global_load_dwordx4 v[32:35], v[64:65], off offset:3072 nt
	global_load_dwordx2 v[78:79], v[68:69], off nt
	global_load_dwordx2 v[74:75], v[68:69], off offset:512 nt
	global_load_dwordx2 v[70:71], v[68:69], off offset:1024 nt
	global_load_dwordx2 v[66:67], v[68:69], off offset:1536 nt
	global_load_dwordx2 v[76:77], v[128:129], off nt
	global_load_dwordx2 v[72:73], v[128:129], off offset:512 nt
	s_nop 0
	global_load_dwordx2 v[68:69], v[128:129], off offset:1024 nt
	global_load_dwordx2 v[64:65], v[128:129], off offset:1536 nt
	s_cmpk_gt_i32 s6, 0x7fff
	s_waitcnt vmcnt(27)
	v_mov_b32_e32 v128, v89
	v_mov_b32_e32 v129, v90
	v_mov_b32_e32 v89, v91
	s_waitcnt vmcnt(26)
	v_mov_b32_e32 v90, v93
	v_mov_b32_e32 v91, v94
	v_mov_b32_e32 v93, v95
	v_pk_add_f32 v[88:89], v[128:129], v[88:89]
	v_pk_add_f32 v[90:91], v[90:91], v[92:93]
	v_add_f32_e32 v88, v88, v89
	v_add_f32_e32 v89, v90, v91
	ds_bpermute_b32 v91, v84, v89
	ds_bpermute_b32 v90, v84, v88
	s_waitcnt vmcnt(25)
	v_add_f32_e32 v92, v96, v97
	v_add_f32_e32 v93, v98, v99
	s_waitcnt vmcnt(24)
	v_add_f32_e32 v94, v100, v101
	s_waitcnt lgkmcnt(1)
	v_add_f32_e32 v91, v89, v91
	v_add_f32_e32 v95, v102, v103
	v_add_f32_e32 v92, v92, v93
	s_waitcnt lgkmcnt(0)
	v_add_f32_e32 v96, v88, v90
	ds_bpermute_b32 v97, v85, v91
	v_add_f32_e32 v93, v94, v95
	ds_bpermute_b32 v94, v84, v92
	ds_bpermute_b32 v98, v85, v96
	ds_bpermute_b32 v95, v84, v93
	s_waitcnt lgkmcnt(3)
	v_add_f32_e32 v91, v91, v97
	v_fmamk_f32 v91, v91, 0x3a800000, v86
	s_waitcnt lgkmcnt(2)
	v_add_f32_e32 v88, v92, v94
	s_waitcnt lgkmcnt(1)
	v_add_f32_e32 v92, v96, v98
	s_waitcnt lgkmcnt(0)
	v_add_f32_e32 v90, v93, v95
	v_fmamk_f32 v92, v92, 0x3a800000, v86
	v_mul_f32_e32 v93, 0x4f800000, v91
	v_cmp_gt_f32_e32 vcc, s11, v91
	v_mul_f32_e32 v94, 0x4f800000, v92
	v_cmp_gt_f32_e64 s[0:1], s11, v92
	v_cndmask_b32_e32 v93, v91, v93, vcc
	v_sqrt_f32_e32 v95, v93
	v_cndmask_b32_e64 v92, v92, v94, s[0:1]
	v_sqrt_f32_e32 v94, v92
	ds_bpermute_b32 v89, v85, v88
	v_add_u32_e32 v96, -1, v95
	v_fma_f32 v100, -v96, v95, v93
	v_add_u32_e32 v98, -1, v94
	v_add_u32_e32 v97, 1, v95
	v_fma_f32 v102, -v98, v94, v92
	v_cmp_ge_f32_e64 s[2:3], 0, v100
	v_add_u32_e32 v99, 1, v94
	v_fma_f32 v101, -v97, v95, v93
	v_cndmask_b32_e64 v95, v95, v96, s[2:3]
	v_cmp_ge_f32_e64 s[2:3], 0, v102
	v_fma_f32 v103, -v99, v94, v92
	s_waitcnt vmcnt(18)
	v_lshlrev_b32_e32 v102, 16, v121
	v_cndmask_b32_e64 v94, v94, v98, s[2:3]
	v_cmp_lt_f32_e64 s[2:3], 0, v101
	v_lshl_add_u64 v[100:101], v[62:63], 0, s[8:9]
	ds_bpermute_b32 v91, v85, v90
	v_cndmask_b32_e64 v95, v95, v97, s[2:3]
	v_mul_f32_e32 v96, 0x37800000, v95
	v_cndmask_b32_e32 v95, v95, v96, vcc
	v_cmp_class_f32_e32 vcc, v93, v87
	v_cmp_lt_f32_e64 s[2:3], 0, v103
	v_and_b32_e32 v103, 0xffff0000, v121
	v_cndmask_b32_e32 v93, v95, v93, vcc
	v_cndmask_b32_e64 v94, v94, v99, s[2:3]
	v_div_scale_f32 v95, s[2:3], v93, v93, 1.0
	v_rcp_f32_e32 v96, v95
	v_mul_f32_e32 v97, 0x37800000, v94
	v_cndmask_b32_e64 v94, v94, v97, s[0:1]
	v_div_scale_f32 v97, vcc, 1.0, v93, 1.0
	v_fma_f32 v98, -v95, v96, 1.0
	v_fmac_f32_e32 v96, v98, v96
	v_mul_f32_e32 v98, v97, v96
	v_cmp_class_f32_e64 s[0:1], v92, v87
	v_fma_f32 v99, -v95, v98, v97
	v_fmac_f32_e32 v98, v99, v96
	v_cndmask_b32_e64 v92, v94, v92, s[0:1]
	v_div_scale_f32 v94, s[0:1], v92, v92, 1.0
	v_fma_f32 v95, -v95, v98, v97
	v_rcp_f32_e32 v97, v94
	v_div_fmas_f32 v95, v95, v96, v98
	v_div_fixup_f32 v96, v95, v93, 1.0
	v_fma_f32 v93, -v94, v97, 1.0
	v_fmac_f32_e32 v97, v93, v97
	v_div_scale_f32 v93, vcc, 1.0, v92, 1.0
	v_mul_f32_e32 v95, v93, v97
	v_fma_f32 v98, -v94, v95, v93
	v_fmac_f32_e32 v95, v98, v97
	v_fma_f32 v93, -v94, v95, v93
	v_div_fmas_f32 v93, v93, v97, v95
	v_div_fixup_f32 v98, v93, v92, 1.0
	s_waitcnt vmcnt(14)
	v_lshlrev_b32_e32 v92, 16, v126
	v_and_b32_e32 v93, 0xffff0000, v126
	v_pk_mul_f32 v[92:93], v[98:99], v[92:93] op_sel_hi:[0,1]
	v_lshlrev_b32_e32 v94, 16, v120
	v_and_b32_e32 v95, 0xffff0000, v120
	s_waitcnt vmcnt(12)
	v_pk_fma_f32 v[92:93], v[28:29], v[92:93], v[112:113]
	v_pk_mul_f32 v[94:95], v[96:97], v[94:95] op_sel_hi:[0,1]
	v_pk_fma_f32 v[92:93], v[20:21], v[94:95], v[92:93]
	v_lshlrev_b32_e32 v94, 16, v127
	v_and_b32_e32 v95, 0xffff0000, v127
	v_pk_mul_f32 v[94:95], v[98:99], v[94:95] op_sel_hi:[0,1]
	v_pk_fma_f32 v[94:95], v[30:31], v[94:95], v[114:115]
	v_pk_mul_f32 v[102:103], v[96:97], v[102:103] op_sel_hi:[0,1]
	v_pk_fma_f32 v[94:95], v[22:23], v[102:103], v[94:95]
	global_store_dwordx4 v[100:101], v[92:95], off sc1 nt
	v_lshlrev_b32_e32 v102, 16, v119
	v_and_b32_e32 v103, 0xffff0000, v119
	v_lshlrev_b32_e32 v92, 16, v124
	v_and_b32_e32 v93, 0xffff0000, v124
	v_pk_mul_f32 v[92:93], v[98:99], v[92:93] op_sel_hi:[0,1]
	v_lshlrev_b32_e32 v94, 16, v118
	v_and_b32_e32 v95, 0xffff0000, v118
	v_pk_fma_f32 v[92:93], v[24:25], v[92:93], v[108:109]
	v_pk_mul_f32 v[94:95], v[96:97], v[94:95] op_sel_hi:[0,1]
	v_pk_fma_f32 v[92:93], v[16:17], v[94:95], v[92:93]
	v_lshlrev_b32_e32 v94, 16, v125
	v_and_b32_e32 v95, 0xffff0000, v125
	v_pk_mul_f32 v[94:95], v[98:99], v[94:95] op_sel_hi:[0,1]
	v_pk_fma_f32 v[94:95], v[26:27], v[94:95], v[110:111]
	v_pk_mul_f32 v[102:103], v[96:97], v[102:103] op_sel_hi:[0,1]
	v_pk_fma_f32 v[94:95], v[18:19], v[102:103], v[94:95]
	global_store_dwordx4 v[100:101], v[92:95], off offset:1024 sc1 nt
	v_lshlrev_b32_e32 v102, 16, v117
	v_and_b32_e32 v103, 0xffff0000, v117
	v_lshlrev_b32_e32 v92, 16, v122
	v_and_b32_e32 v93, 0xffff0000, v122
	v_pk_mul_f32 v[92:93], v[98:99], v[92:93] op_sel_hi:[0,1]
	v_lshlrev_b32_e32 v94, 16, v116
	v_and_b32_e32 v95, 0xffff0000, v116
	v_pk_fma_f32 v[92:93], v[12:13], v[92:93], v[104:105]
	v_pk_mul_f32 v[94:95], v[96:97], v[94:95] op_sel_hi:[0,1]
	v_pk_fma_f32 v[92:93], v[4:5], v[94:95], v[92:93]
	v_lshlrev_b32_e32 v94, 16, v123
	v_and_b32_e32 v95, 0xffff0000, v123
	v_pk_mul_f32 v[94:95], v[98:99], v[94:95] op_sel_hi:[0,1]
	v_pk_fma_f32 v[94:95], v[14:15], v[94:95], v[106:107]
	v_pk_mul_f32 v[102:103], v[96:97], v[102:103] op_sel_hi:[0,1]
	v_pk_fma_f32 v[94:95], v[6:7], v[102:103], v[94:95]
	global_store_dwordx4 v[100:101], v[92:95], off offset:2048 sc1 nt
	s_nop 1
	v_lshlrev_b32_e32 v92, 16, v82
	v_and_b32_e32 v93, 0xffff0000, v82
	v_pk_mul_f32 v[92:93], v[98:99], v[92:93] op_sel_hi:[0,1]
	v_lshlrev_b32_e32 v82, 16, v83
	v_and_b32_e32 v83, 0xffff0000, v83
	v_pk_fma_f32 v[48:49], v[8:9], v[92:93], v[48:49]
	v_lshlrev_b32_e32 v92, 16, v80
	v_and_b32_e32 v93, 0xffff0000, v80
	v_pk_mul_f32 v[82:83], v[98:99], v[82:83] op_sel_hi:[0,1]
	v_lshlrev_b32_e32 v80, 16, v81
	v_and_b32_e32 v81, 0xffff0000, v81
	v_pk_mul_f32 v[92:93], v[96:97], v[92:93] op_sel_hi:[0,1]
	v_pk_fma_f32 v[50:51], v[10:11], v[82:83], v[50:51]
	v_pk_mul_f32 v[80:81], v[96:97], v[80:81] op_sel_hi:[0,1]
	v_pk_fma_f32 v[48:49], v[0:1], v[92:93], v[48:49]
	v_pk_fma_f32 v[50:51], v[2:3], v[80:81], v[50:51]
	global_store_dwordx4 v[100:101], v[48:51], off offset:3072 sc1 nt
	s_cbranch_scc1 .LBB0_1034
	s_waitcnt lgkmcnt(0)
	v_add_f32_e32 v48, v90, v91
	v_fmamk_f32 v48, v48, 0x3a800000, v86
	v_mul_f32_e32 v49, 0x4f800000, v48
	v_cmp_gt_f32_e32 vcc, s11, v48
	v_add_f32_e32 v81, v88, v89
	v_fmamk_f32 v81, v81, 0x3a800000, v86
	v_cndmask_b32_e32 v48, v48, v49, vcc
	v_sqrt_f32_e32 v49, v48
	v_mul_f32_e32 v82, 0x4f800000, v81
	s_ashr_i32 s7, s6, 31
	v_add_u32_e32 v50, -1, v49
	v_fma_f32 v80, -v50, v49, v48
	v_add_u32_e32 v51, 1, v49
	v_cmp_ge_f32_e64 s[0:1], 0, v80
	s_nop 1
	v_cndmask_b32_e64 v50, v49, v50, s[0:1]
	v_fma_f32 v49, -v51, v49, v48
	v_cmp_lt_f32_e64 s[0:1], 0, v49
	s_nop 1
	v_cndmask_b32_e64 v49, v50, v51, s[0:1]
	v_mul_f32_e32 v50, 0x37800000, v49
	v_cndmask_b32_e32 v49, v49, v50, vcc
	v_cmp_class_f32_e32 vcc, v48, v87
	s_nop 1
	v_cndmask_b32_e32 v48, v49, v48, vcc
	v_div_scale_f32 v49, s[0:1], v48, v48, 1.0
	v_rcp_f32_e32 v50, v49
	v_cmp_gt_f32_e64 s[0:1], s11, v81
	v_fma_f32 v51, -v49, v50, 1.0
	s_nop 0
	v_cndmask_b32_e64 v81, v81, v82, s[0:1]
	v_fmac_f32_e32 v50, v51, v50
	v_div_scale_f32 v51, vcc, 1.0, v48, 1.0
	v_sqrt_f32_e32 v82, v81
	v_mul_f32_e32 v80, v51, v50
	v_fma_f32 v83, -v49, v80, v51
	v_fmac_f32_e32 v80, v83, v50
	v_fma_f32 v49, -v49, v80, v51
	v_add_u32_e32 v51, -1, v82
	v_fma_f32 v83, -v51, v82, v81
	v_cmp_ge_f32_e64 s[2:3], 0, v83
	v_add_u32_e32 v83, 1, v82
	v_div_fmas_f32 v49, v49, v50, v80
	v_cndmask_b32_e64 v51, v82, v51, s[2:3]
	v_fma_f32 v82, -v83, v82, v81
	v_cmp_lt_f32_e64 s[2:3], 0, v82
	v_div_fixup_f32 v48, v49, v48, 1.0
	s_nop 0
	v_cndmask_b32_e64 v51, v51, v83, s[2:3]
	v_mul_f32_e32 v82, 0x37800000, v51
	v_cndmask_b32_e64 v51, v51, v82, s[0:1]
	v_cmp_class_f32_e64 s[0:1], v81, v87
	s_waitcnt vmcnt(11)
	v_and_b32_e32 v83, 0xffff0000, v78
	v_cndmask_b32_e64 v51, v51, v81, s[0:1]
	v_div_scale_f32 v81, s[0:1], v51, v51, 1.0
	v_rcp_f32_e32 v82, v81
	s_lshl_b64 s[0:1], s[6:7], 12
	v_fma_f32 v49, -v81, v82, 1.0
	v_fmac_f32_e32 v82, v49, v82
	v_div_scale_f32 v49, vcc, 1.0, v51, 1.0
	v_mul_f32_e32 v50, v49, v82
	v_fma_f32 v80, -v81, v50, v49
	v_fmac_f32_e32 v50, v80, v82
	v_fma_f32 v49, -v81, v50, v49
	v_div_fmas_f32 v49, v49, v82, v50
	v_div_fixup_f32 v50, v49, v51, 1.0
	v_lshlrev_b32_e32 v82, 16, v78
	v_pk_mul_f32 v[82:83], v[50:51], v[82:83] op_sel_hi:[0,1]
	v_lshlrev_b32_e32 v78, 16, v79
	v_and_b32_e32 v79, 0xffff0000, v79
	v_pk_fma_f32 v[44:45], v[28:29], v[82:83], v[44:45]
	s_waitcnt vmcnt(7)
	v_lshlrev_b32_e32 v82, 16, v76
	v_and_b32_e32 v83, 0xffff0000, v76
	v_pk_mul_f32 v[78:79], v[50:51], v[78:79] op_sel_hi:[0,1]
	v_lshlrev_b32_e32 v76, 16, v77
	v_and_b32_e32 v77, 0xffff0000, v77
	v_pk_mul_f32 v[82:83], v[48:49], v[82:83] op_sel_hi:[0,1]
	v_pk_fma_f32 v[46:47], v[30:31], v[78:79], v[46:47]
	v_pk_mul_f32 v[76:77], v[48:49], v[76:77] op_sel_hi:[0,1]
	v_lshl_add_u64 v[80:81], v[62:63], 0, s[0:1]
	v_pk_fma_f32 v[44:45], v[20:21], v[82:83], v[44:45]
	v_pk_fma_f32 v[46:47], v[22:23], v[76:77], v[46:47]
	global_store_dwordx4 v[80:81], v[44:47], off sc1 nt
	s_nop 1
	v_lshlrev_b32_e32 v44, 16, v74
	v_and_b32_e32 v45, 0xffff0000, v74
	v_pk_mul_f32 v[44:45], v[50:51], v[44:45] op_sel_hi:[0,1]
	v_pk_fma_f32 v[40:41], v[24:25], v[44:45], v[40:41]
	s_waitcnt vmcnt(7)
	v_lshlrev_b32_e32 v44, 16, v72
	v_and_b32_e32 v45, 0xffff0000, v72
	v_pk_mul_f32 v[44:45], v[48:49], v[44:45] op_sel_hi:[0,1]
	v_pk_fma_f32 v[40:41], v[16:17], v[44:45], v[40:41]
	v_lshlrev_b32_e32 v44, 16, v75
	v_and_b32_e32 v45, 0xffff0000, v75
	v_pk_mul_f32 v[44:45], v[50:51], v[44:45] op_sel_hi:[0,1]
	v_pk_fma_f32 v[42:43], v[26:27], v[44:45], v[42:43]
	v_lshlrev_b32_e32 v44, 16, v73
	v_and_b32_e32 v45, 0xffff0000, v73
	v_pk_mul_f32 v[44:45], v[48:49], v[44:45] op_sel_hi:[0,1]
	v_pk_fma_f32 v[42:43], v[18:19], v[44:45], v[42:43]
	global_store_dwordx4 v[80:81], v[40:43], off offset:1024 sc1 nt
	s_nop 1
	v_lshlrev_b32_e32 v40, 16, v70
	v_and_b32_e32 v41, 0xffff0000, v70
	v_pk_mul_f32 v[40:41], v[50:51], v[40:41] op_sel_hi:[0,1]
	v_pk_fma_f32 v[36:37], v[12:13], v[40:41], v[36:37]
	s_waitcnt vmcnt(7)
	v_lshlrev_b32_e32 v40, 16, v68
	v_and_b32_e32 v41, 0xffff0000, v68
	v_pk_mul_f32 v[40:41], v[48:49], v[40:41] op_sel_hi:[0,1]
	v_pk_fma_f32 v[36:37], v[4:5], v[40:41], v[36:37]
	v_lshlrev_b32_e32 v40, 16, v71
	v_and_b32_e32 v41, 0xffff0000, v71
	v_pk_mul_f32 v[40:41], v[50:51], v[40:41] op_sel_hi:[0,1]
	v_pk_fma_f32 v[38:39], v[14:15], v[40:41], v[38:39]
	v_lshlrev_b32_e32 v40, 16, v69
	v_and_b32_e32 v41, 0xffff0000, v69
	v_pk_mul_f32 v[40:41], v[48:49], v[40:41] op_sel_hi:[0,1]
	v_pk_fma_f32 v[38:39], v[6:7], v[40:41], v[38:39]
	global_store_dwordx4 v[80:81], v[36:39], off offset:2048 sc1 nt
	s_nop 1
	v_lshlrev_b32_e32 v36, 16, v66
	v_and_b32_e32 v37, 0xffff0000, v66
	v_pk_mul_f32 v[36:37], v[50:51], v[36:37] op_sel_hi:[0,1]
	v_pk_fma_f32 v[32:33], v[8:9], v[36:37], v[32:33]
	s_waitcnt vmcnt(7)
	v_lshlrev_b32_e32 v36, 16, v64
	v_and_b32_e32 v37, 0xffff0000, v64
	v_pk_mul_f32 v[36:37], v[48:49], v[36:37] op_sel_hi:[0,1]
	v_pk_fma_f32 v[32:33], v[0:1], v[36:37], v[32:33]
	v_lshlrev_b32_e32 v36, 16, v67
	v_and_b32_e32 v37, 0xffff0000, v67
	v_pk_mul_f32 v[36:37], v[50:51], v[36:37] op_sel_hi:[0,1]
	v_pk_fma_f32 v[34:35], v[10:11], v[36:37], v[34:35]
	v_lshlrev_b32_e32 v36, 16, v65
	v_and_b32_e32 v37, 0xffff0000, v65
	v_pk_mul_f32 v[36:37], v[48:49], v[36:37] op_sel_hi:[0,1]
	v_pk_fma_f32 v[34:35], v[2:3], v[36:37], v[34:35]
	global_store_dwordx4 v[80:81], v[32:35], off offset:3072 sc1 nt
	s_branch .LBB0_1034
